# instruction selection: attention l-sum as v_pk_add_f32 tree (17 instead of 32 VALU), exps in place
# speedup vs baseline: 1.0093x; 1.0093x over previous
; #define AT_PK(P, B) cvtpk_s(P[B], P[B + 1])
; template <int THRL>
; __device__ __forceinline__ void attn_item(int b, int h, int s, const bf16_t* Q, const bf16_t* KN, const bf16_t* KR, const bf16_t* V, const float* goa  , bf16_t* Y, float* ssqy, AT_LAS char* shm, int wid0) {
;     ...
;                 float sacc = 0.f;
; #pragma unroll
;                 for (int r = 0; r < 16; ++r) { p0[r] = __builtin_amdgcn_exp2f(p0[r]); p1[r] = __builtin_amdgcn_exp2f(p1[r]); sacc += p0[r] + p1[r]; }
;                 l_reg += sacc;
;     ...
;                 pw0 = (u32x4){AT_PK(p0, 0), AT_PK(p0, 2), AT_PK(p0, 4), AT_PK(p0, 6)}; pw1 = (u32x4){AT_PK(p0, 8), AT_PK(p0, 10), AT_PK(p0, 12), AT_PK(p0, 14)};
;                 pw2 = (u32x4){AT_PK(p1, 0), AT_PK(p1, 2), AT_PK(p1, 4), AT_PK(p1, 6)}; pw3 = (u32x4){AT_PK(p1, 8), AT_PK(p1, 10), AT_PK(p1, 12), AT_PK(p1, 14)};
;     ...
;                 if (late) have = true;
;                 else pv(o, vp0 + (t & 3) * VSLOTB, pw0, pw1, pw2, pw3);
;             }
;             if (!late) { if (t + 1 < NT && (jb + 1) <= wq) qkt(p0, p1, kp0 + ((t + 1) & 3) * KSLOTB, qr, negm); }
.LBB13_779:
	v_exp_f32_e32 v18, v18
	v_exp_f32_e32 v34, v34
	v_exp_f32_e32 v19, v19
	v_exp_f32_e32 v35, v35
	v_exp_f32_e32 v20, v20
	v_exp_f32_e32 v36, v36
	v_exp_f32_e32 v21, v21
	v_exp_f32_e32 v37, v37
	v_exp_f32_e32 v22, v22
	v_exp_f32_e32 v38, v38
	v_exp_f32_e32 v23, v23
	v_exp_f32_e32 v39, v39
	v_exp_f32_e32 v24, v24
	v_exp_f32_e32 v40, v40
	v_exp_f32_e32 v25, v25
	v_exp_f32_e32 v41, v41
	v_exp_f32_e32 v26, v26
	v_exp_f32_e32 v42, v42
	v_exp_f32_e32 v27, v27
	v_exp_f32_e32 v43, v43
	v_exp_f32_e32 v28, v28
	v_exp_f32_e32 v44, v44
	v_exp_f32_e32 v29, v29
	v_exp_f32_e32 v45, v45
	v_exp_f32_e32 v30, v30
	v_exp_f32_e32 v46, v46
	v_exp_f32_e32 v31, v31
	v_exp_f32_e32 v47, v47
	v_exp_f32_e32 v32, v32
	v_exp_f32_e32 v48, v48
	v_exp_f32_e32 v33, v33
	v_exp_f32_e32 v49, v49
	v_cvt_pk_bf16_f32 v110, v18, v19
	v_cvt_pk_bf16_f32 v111, v20, v21
	v_cvt_pk_bf16_f32 v112, v22, v23
	v_cvt_pk_bf16_f32 v113, v24, v25
	v_cvt_pk_bf16_f32 v106, v26, v27
	v_cvt_pk_bf16_f32 v107, v28, v29
	v_cvt_pk_bf16_f32 v108, v30, v31
	v_cvt_pk_bf16_f32 v109, v32, v33
	v_cvt_pk_bf16_f32 v118, v34, v35
	v_cvt_pk_bf16_f32 v119, v36, v37
	v_cvt_pk_bf16_f32 v120, v38, v39
	v_cvt_pk_bf16_f32 v121, v40, v41
	v_cvt_pk_bf16_f32 v114, v42, v43
	v_cvt_pk_bf16_f32 v115, v44, v45
	v_cvt_pk_bf16_f32 v116, v46, v47
	s_and_b64 vcc, exec, s[76:77]
	v_cvt_pk_bf16_f32 v117, v48, v49
	s_cbranch_vccnz .LBB13_781
	v_pk_add_f32 v[18:19], v[18:19], v[34:35]
	v_pk_add_f32 v[20:21], v[20:21], v[36:37]
	v_pk_add_f32 v[22:23], v[22:23], v[38:39]
	v_pk_add_f32 v[24:25], v[24:25], v[40:41]
	v_pk_add_f32 v[26:27], v[26:27], v[42:43]
	v_pk_add_f32 v[28:29], v[28:29], v[44:45]
	v_pk_add_f32 v[30:31], v[30:31], v[46:47]
	v_pk_add_f32 v[32:33], v[32:33], v[48:49]
	v_pk_add_f32 v[18:19], v[18:19], v[20:21]
	v_pk_add_f32 v[22:23], v[22:23], v[24:25]
	v_pk_add_f32 v[26:27], v[26:27], v[28:29]
	v_pk_add_f32 v[30:31], v[30:31], v[32:33]
	v_pk_add_f32 v[18:19], v[18:19], v[22:23]
	v_pk_add_f32 v[26:27], v[26:27], v[30:31]
	v_pk_add_f32 v[18:19], v[18:19], v[26:27]
	s_nop 0
	v_add_f32_e32 v18, v18, v19
	v_add_f32_e32 v153, v153, v18
	s_add_i32 s92, s9, -2
	s_cmp_lt_u32 s92, s79
	s_cselect_b64 vcc, -1, 0
	s_cmp_lt_i32 s84, s2
	s_cselect_b64 s[88:89], -1, 0
	s_and_b64 s[88:89], vcc, s[88:89]
	s_andn2_b64 vcc, exec, s[88:89]
	s_cbranch_vccnz .Lat0_e_pvonly
	s_and_b32 s84, s92, 3
	s_mulk_i32 s84, 0x3000
	v_add_u32_e32 v215, s84, v190
	s_waitcnt lgkmcnt(0)
	ds_read_b64_tr_b16 v[248:249], v214 offset:56320
	ds_read_b64_tr_b16 v[250:251], v214 offset:56832
	ds_read_b128 v[198:201], v215 offset:8192
	ds_read_b128 v[202:205], v215 offset:8704
	ds_read_b128 v[206:209], v215 offset:10240
	ds_read_b128 v[210:213], v215 offset:10752
	s_waitcnt lgkmcnt(6)
	v_mfma_f32_32x32x16_bf16 v[50:65], v[110:113], v[216:219], v[50:65]
	v_add_u32_e32 v236, s84, v252
	ds_read_b128 v[34:37], v236
	v_mfma_f32_32x32x16_bf16 v[50:65], v[106:109], v[220:223], v[50:65]
	ds_read_b128 v[154:157], v236 offset:4096
	v_mfma_f32_32x32x16_bf16 v[50:65], v[118:121], v[224:227], v[50:65]
	v_add_u32_e32 v239, s84, v253
	ds_read_b128 v[158:161], v239
	v_mfma_f32_32x32x16_bf16 v[50:65], v[114:117], v[228:231], v[50:65]
	ds_read_b128 v[162:165], v239 offset:4096
	v_mfma_f32_32x32x16_bf16 v[2:17], v[110:113], v[232:235], v[2:17]
	v_add_u32_e32 v236, s84, v254
	ds_read_b128 v[166:169], v236
	v_mfma_f32_32x32x16_bf16 v[2:17], v[106:109], v[240:243], v[2:17]
	ds_read_b128 v[170:173], v236 offset:4096
	v_mfma_f32_32x32x16_bf16 v[2:17], v[118:121], v[244:247], v[2:17]
	v_add_u32_e32 v239, s84, v255
	ds_read_b128 v[174:177], v239
	s_waitcnt lgkmcnt(11)
	v_mfma_f32_32x32x16_bf16 v[2:17], v[114:117], v[248:251], v[2:17]
	ds_read_b128 v[178:181], v239 offset:4096
	s_waitcnt lgkmcnt(7)
	v_mfma_f32_32x32x16_bf16 v[18:33], v[34:37], v[82:85], v[66:81]
	s_waitcnt lgkmcnt(6)
	v_mfma_f32_32x32x16_bf16 v[34:49], v[154:157], v[82:85], v[66:81]
	s_waitcnt lgkmcnt(5)
	v_mfma_f32_32x32x16_bf16 v[18:33], v[158:161], v[86:89], v[18:33]
	s_waitcnt lgkmcnt(4)
	v_mfma_f32_32x32x16_bf16 v[34:49], v[162:165], v[86:89], v[34:49]
	s_waitcnt lgkmcnt(3)
	v_mfma_f32_32x32x16_bf16 v[18:33], v[166:169], v[90:93], v[18:33]
	s_waitcnt lgkmcnt(2)
	v_mfma_f32_32x32x16_bf16 v[34:49], v[170:173], v[90:93], v[34:49]
	s_waitcnt lgkmcnt(1)
	v_mfma_f32_32x32x16_bf16 v[18:33], v[174:177], v[94:97], v[18:33]
	s_waitcnt lgkmcnt(0)
	v_mfma_f32_32x32x16_bf16 v[34:49], v[178:181], v[94:97], v[34:49]
	v_mfma_f32_32x32x16_bf16 v[18:33], v[198:201], v[98:101], v[18:33]
	v_mfma_f32_32x32x16_bf16 v[34:49], v[202:205], v[98:101], v[34:49]
	v_mfma_f32_32x32x16_bf16 v[18:33], v[206:209], v[102:105], v[18:33]
	v_mfma_f32_32x32x16_bf16 v[34:49], v[210:213], v[102:105], v[34:49]
	s_branch .LBB13_764

; template <int THRL>
; __device__ __forceinline__ void attn_item(int b, int h, int s, const bf16_t* Q, const bf16_t* KN, const bf16_t* KR, const bf16_t* V, const float* goa  , bf16_t* Y, float* ssqy, AT_LAS char* shm, int wid0) {
;     ...
;                 float sacc = 0.f;
; #pragma unroll
;                 for (int r = 0; r < 16; ++r) { p0[r] = __builtin_amdgcn_exp2f(p0[r]); p1[r] = __builtin_amdgcn_exp2f(p1[r]); sacc += p0[r] + p1[r]; }
;                 l_reg += sacc;
.LBB13_782:
	v_pk_add_f32 v[18:19], v[18:19], v[34:35]
	v_pk_add_f32 v[20:21], v[20:21], v[36:37]
	v_pk_add_f32 v[22:23], v[22:23], v[38:39]
	v_pk_add_f32 v[24:25], v[24:25], v[40:41]
	v_pk_add_f32 v[26:27], v[26:27], v[42:43]
	v_pk_add_f32 v[28:29], v[28:29], v[44:45]
	v_pk_add_f32 v[30:31], v[30:31], v[46:47]
	v_pk_add_f32 v[32:33], v[32:33], v[48:49]
	v_pk_add_f32 v[18:19], v[18:19], v[20:21]
	v_pk_add_f32 v[22:23], v[22:23], v[24:25]
	v_pk_add_f32 v[26:27], v[26:27], v[28:29]
	v_pk_add_f32 v[30:31], v[30:31], v[32:33]
	v_pk_add_f32 v[18:19], v[18:19], v[22:23]
	v_pk_add_f32 v[26:27], v[26:27], v[30:31]
	v_pk_add_f32 v[18:19], v[18:19], v[26:27]
	s_nop 0
	v_add_f32_e32 v18, v18, v19
	v_add_f32_e32 v153, v153, v18
	s_and_b64 vcc, exec, s[76:77]
	s_cbranch_vccnz .LBB13_764

; #define AT_PK(P, B) cvtpk_s(P[B], P[B + 1])
; template <int THRL>
; __device__ __forceinline__ void attn_item(int b, int h, int s, const bf16_t* Q, const bf16_t* KN, const bf16_t* KR, const bf16_t* V, const float* goa  , bf16_t* Y, float* ssqy, AT_LAS char* shm, int wid0) {
;     ...
;                 float sacc = 0.f;
; #pragma unroll
;                 for (int r = 0; r < 16; ++r) { p0[r] = __builtin_amdgcn_exp2f(p0[r]); p1[r] = __builtin_amdgcn_exp2f(p1[r]); sacc += p0[r] + p1[r]; }
;                 l_reg += sacc;
;     ...
;                 pw0 = (u32x4){AT_PK(p0, 0), AT_PK(p0, 2), AT_PK(p0, 4), AT_PK(p0, 6)}; pw1 = (u32x4){AT_PK(p0, 8), AT_PK(p0, 10), AT_PK(p0, 12), AT_PK(p0, 14)};
;                 pw2 = (u32x4){AT_PK(p1, 0), AT_PK(p1, 2), AT_PK(p1, 4), AT_PK(p1, 6)}; pw3 = (u32x4){AT_PK(p1, 8), AT_PK(p1, 10), AT_PK(p1, 12), AT_PK(p1, 14)};
;     ...
;                 if (late) have = true;
;                 else pv(o, vp0 + (t & 3) * VSLOTB, pw0, pw1, pw2, pw3);
;             }
;             if (!late) { if (t + 1 < NT && (jb + 1) <= wq) qkt(p0, p1, kp0 + ((t + 1) & 3) * KSLOTB, qr, negm); }
.LBB13_1757:
	v_exp_f32_e32 v18, v18
	v_exp_f32_e32 v34, v34
	v_exp_f32_e32 v19, v19
	v_exp_f32_e32 v35, v35
	v_exp_f32_e32 v20, v20
	v_exp_f32_e32 v36, v36
	v_exp_f32_e32 v21, v21
	v_exp_f32_e32 v37, v37
	v_exp_f32_e32 v22, v22
	v_exp_f32_e32 v38, v38
	v_exp_f32_e32 v23, v23
	v_exp_f32_e32 v39, v39
	v_exp_f32_e32 v24, v24
	v_exp_f32_e32 v40, v40
	v_exp_f32_e32 v25, v25
	v_exp_f32_e32 v41, v41
	v_exp_f32_e32 v26, v26
	v_exp_f32_e32 v42, v42
	v_exp_f32_e32 v27, v27
	v_exp_f32_e32 v43, v43
	v_exp_f32_e32 v28, v28
	v_exp_f32_e32 v44, v44
	v_exp_f32_e32 v29, v29
	v_exp_f32_e32 v45, v45
	v_exp_f32_e32 v30, v30
	v_exp_f32_e32 v46, v46
	v_exp_f32_e32 v31, v31
	v_exp_f32_e32 v47, v47
	v_exp_f32_e32 v32, v32
	v_exp_f32_e32 v48, v48
	v_exp_f32_e32 v33, v33
	v_exp_f32_e32 v49, v49
	v_cvt_pk_bf16_f32 v110, v18, v19
	v_cvt_pk_bf16_f32 v111, v20, v21
	v_cvt_pk_bf16_f32 v112, v22, v23
	v_cvt_pk_bf16_f32 v113, v24, v25
	v_cvt_pk_bf16_f32 v106, v26, v27
	v_cvt_pk_bf16_f32 v107, v28, v29
	v_cvt_pk_bf16_f32 v108, v30, v31
	v_cvt_pk_bf16_f32 v109, v32, v33
	v_cvt_pk_bf16_f32 v118, v34, v35
	v_cvt_pk_bf16_f32 v119, v36, v37
	v_cvt_pk_bf16_f32 v120, v38, v39
	v_cvt_pk_bf16_f32 v121, v40, v41
	v_cvt_pk_bf16_f32 v114, v42, v43
	v_cvt_pk_bf16_f32 v115, v44, v45
	v_cvt_pk_bf16_f32 v116, v46, v47
	s_and_b64 vcc, exec, s[76:77]
	v_cvt_pk_bf16_f32 v117, v48, v49
	s_cbranch_vccnz .LBB13_1759
	v_pk_add_f32 v[18:19], v[18:19], v[34:35]
	v_pk_add_f32 v[20:21], v[20:21], v[36:37]
	v_pk_add_f32 v[22:23], v[22:23], v[38:39]
	v_pk_add_f32 v[24:25], v[24:25], v[40:41]
	v_pk_add_f32 v[26:27], v[26:27], v[42:43]
	v_pk_add_f32 v[28:29], v[28:29], v[44:45]
	v_pk_add_f32 v[30:31], v[30:31], v[46:47]
	v_pk_add_f32 v[32:33], v[32:33], v[48:49]
	v_pk_add_f32 v[18:19], v[18:19], v[20:21]
	v_pk_add_f32 v[22:23], v[22:23], v[24:25]
	v_pk_add_f32 v[26:27], v[26:27], v[28:29]
	v_pk_add_f32 v[30:31], v[30:31], v[32:33]
	v_pk_add_f32 v[18:19], v[18:19], v[22:23]
	v_pk_add_f32 v[26:27], v[26:27], v[30:31]
	v_pk_add_f32 v[18:19], v[18:19], v[26:27]
	s_nop 0
	v_add_f32_e32 v18, v18, v19
	v_add_f32_e32 v153, v153, v18
	s_add_i32 s92, s80, -2
	s_cmp_lt_u32 s92, s3
	s_cselect_b64 vcc, -1, 0
	s_cmp_lt_i32 s84, s33
	s_cselect_b64 s[88:89], -1, 0
	s_and_b64 s[88:89], vcc, s[88:89]
	s_andn2_b64 vcc, exec, s[88:89]
	s_cbranch_vccnz .Lat1_e_pvonly
	s_and_b32 s84, s92, 3
	s_mulk_i32 s84, 0x3000
	v_add_u32_e32 v215, s84, v190
	s_waitcnt lgkmcnt(0)
	ds_read_b64_tr_b16 v[248:249], v214 offset:56320
	ds_read_b64_tr_b16 v[250:251], v214 offset:56832
	ds_read_b128 v[198:201], v215 offset:8192
	ds_read_b128 v[202:205], v215 offset:8704
	ds_read_b128 v[206:209], v215 offset:10240
	ds_read_b128 v[210:213], v215 offset:10752
	s_waitcnt lgkmcnt(6)
	v_mfma_f32_32x32x16_bf16 v[50:65], v[110:113], v[216:219], v[50:65]
	v_add_u32_e32 v236, s84, v252
	ds_read_b128 v[34:37], v236
	v_mfma_f32_32x32x16_bf16 v[50:65], v[106:109], v[220:223], v[50:65]
	ds_read_b128 v[154:157], v236 offset:4096
	v_mfma_f32_32x32x16_bf16 v[50:65], v[118:121], v[224:227], v[50:65]
	v_add_u32_e32 v239, s84, v253
	ds_read_b128 v[158:161], v239
	v_mfma_f32_32x32x16_bf16 v[50:65], v[114:117], v[228:231], v[50:65]
	ds_read_b128 v[162:165], v239 offset:4096
	v_mfma_f32_32x32x16_bf16 v[2:17], v[110:113], v[232:235], v[2:17]
	v_add_u32_e32 v236, s84, v254
	ds_read_b128 v[166:169], v236
	v_mfma_f32_32x32x16_bf16 v[2:17], v[106:109], v[240:243], v[2:17]
	ds_read_b128 v[170:173], v236 offset:4096
	v_mfma_f32_32x32x16_bf16 v[2:17], v[118:121], v[244:247], v[2:17]
	v_add_u32_e32 v239, s84, v255
	ds_read_b128 v[174:177], v239
	s_waitcnt lgkmcnt(11)
	v_mfma_f32_32x32x16_bf16 v[2:17], v[114:117], v[248:251], v[2:17]
	ds_read_b128 v[178:181], v239 offset:4096
	s_waitcnt lgkmcnt(7)
	v_mfma_f32_32x32x16_bf16 v[18:33], v[34:37], v[82:85], v[66:81]
	s_waitcnt lgkmcnt(6)
	v_mfma_f32_32x32x16_bf16 v[34:49], v[154:157], v[82:85], v[66:81]
	s_waitcnt lgkmcnt(5)
	v_mfma_f32_32x32x16_bf16 v[18:33], v[158:161], v[86:89], v[18:33]
	s_waitcnt lgkmcnt(4)
	v_mfma_f32_32x32x16_bf16 v[34:49], v[162:165], v[86:89], v[34:49]
	s_waitcnt lgkmcnt(3)
	v_mfma_f32_32x32x16_bf16 v[18:33], v[166:169], v[90:93], v[18:33]
	s_waitcnt lgkmcnt(2)
	v_mfma_f32_32x32x16_bf16 v[34:49], v[170:173], v[90:93], v[34:49]
	s_waitcnt lgkmcnt(1)
	v_mfma_f32_32x32x16_bf16 v[18:33], v[174:177], v[94:97], v[18:33]
	s_waitcnt lgkmcnt(0)
	v_mfma_f32_32x32x16_bf16 v[34:49], v[178:181], v[94:97], v[34:49]
	v_mfma_f32_32x32x16_bf16 v[18:33], v[198:201], v[98:101], v[18:33]
	v_mfma_f32_32x32x16_bf16 v[34:49], v[202:205], v[98:101], v[34:49]
	v_mfma_f32_32x32x16_bf16 v[18:33], v[206:209], v[102:105], v[18:33]
	v_mfma_f32_32x32x16_bf16 v[34:49], v[210:213], v[102:105], v[34:49]
	s_branch .LBB13_1742
